# P3 v15: v13 + folded tail steps + first two DMA stages issued before the address setup (combined)
# speedup vs baseline: 1.0011x; 1.0011x over previous
; #define LAS __attribute__((address_space(3)))
; __device__ __forceinline__ void gla_scan_item(const Ctx& C, int item, LAS unsigned char* lds, int tid) {
;     const int jx = item >> 3, bh = (item & 7) * 4 + (jx >> 3), sl = jx & 7, b = bh >> 2, h = bh & 3;
;     LAS bf16* Aq = (LAS bf16*)lds;
;     LAS bf16* Bc = (LAS bf16*)(lds + 25600);
;     LAS bf16* Kt = (LAS bf16*)(lds + 38400);
;     const int wave = tid >> 6, lane = tid & 63, l15 = lane & 15, quad = lane >> 4;
;     f32x4 S[2] = {(f32x4){0.f, 0.f, 0.f, 0.f}, (f32x4){0.f, 0.f, 0.f, 0.f}};
;     *(LAS u32x4*)(Bc + (tid >> 4) * 200 + (tid & 15) * 8) = (u32x4){0u, 0u, 0u, 0u};
;     u32x4 rq0A, rq1A, rsA, rk0A, rk1A, rvA = (u32x4){0u, 0u, 0u, 0u}; f32x4 rdA;
;     u32x4 rq0B, rq1B, rsB, rk0B, rk1B, rvB = (u32x4){0u, 0u, 0u, 0u}; f32x4 rdB;
;     ...
;     SCAN_LOAD(A, 0); SCAN_LOAD(B, 1);
.LBB0_428:
	s_cmp_lt_i32 s96, 4
	s_cselect_b64 s[4:5], -1, 0
	s_add_u32 s6, s94, 0xb300000
	s_addc_u32 s7, s95, 0
	s_and_b64 s[0:1], s[4:5], s[0:1]
	s_andn2_b64 vcc, exec, s[0:1]
	s_cbranch_vccnz .LBB0_496
	s_cmpk_gt_i32 s2, 0xff
	s_cbranch_scc1 .LBB0_496
	v_readfirstlane_b32 s32, v163
	v_and_b32_e32 v203, 63, v162
	v_and_b32_e32 v202, 15, v162
	v_bfe_u32 v201, v162, 4, 2
	v_lshrrev_b32_e32 v200, 4, v203
	v_lshl_add_u32 v200, v163, 3, v200
	v_and_b32_e32 v199, 15, v200
	v_xor_b32_e32 v199, v199, v202
	v_lshlrev_b32_e32 v255, 10, v200
	v_lshl_add_u32 v255, v199, 4, v255
	v_lshrrev_b32_e32 v200, 4, v203
	v_lshl_add_u32 v200, v163, 3, v200
	v_add_u32_e32 v200, 4, v200
	v_and_b32_e32 v199, 15, v200
	v_xor_b32_e32 v199, v199, v202
	v_lshlrev_b32_e32 v254, 10, v200
	v_lshl_add_u32 v254, v199, 4, v254
	v_lshrrev_b32_e32 v200, 3, v203
	v_lshl_add_u32 v200, v163, 3, v200
	v_bfe_u32 v199, v200, 1, 3
	v_and_b32_e32 v198, 7, v203
	v_xor_b32_e32 v199, v199, v198
	v_lshlrev_b32_e32 v253, 7, v200
	v_lshl_add_u32 v253, v199, 4, v253
	v_lshrrev_b32_e32 v200, 3, v203
	v_lshl_add_u32 v200, v163, 4, v200
	v_bfe_u32 v199, v200, 1, 3
	v_and_b32_e32 v198, 7, v203
	v_xor_b32_e32 v199, v199, v198
	v_lshlrev_b32_e32 v252, 7, v200
	v_lshl_add_u32 v252, v199, 4, v252
	v_lshrrev_b32_e32 v200, 3, v203
	v_lshl_add_u32 v200, v163, 4, v200
	v_add_u32_e32 v200, 8, v200
	v_bfe_u32 v199, v200, 1, 3
	v_and_b32_e32 v198, 7, v203
	v_xor_b32_e32 v199, v199, v198
	v_lshlrev_b32_e32 v251, 7, v200
	v_lshl_add_u32 v251, v199, 4, v251
	s_lshl_b32 s46, s32, 11
	s_lshl_b32 s47, s32, 10
	s_add_i32 s47, s47, 0x4000
	s_add_i32 s48, s46, 0x6000
	s_mov_b32 s3, s2
	s_lshr_b32 s4, s3, 3
	s_and_b32 s41, s4, 7
	s_lshr_b32 s5, s4, 3
	s_and_b32 s37, s3, 7
	s_lshl_b32 s37, s37, 2
	s_add_i32 s37, s37, s5
	s_lshr_b32 s39, s37, 2
	s_and_b32 s40, s37, 3
	s_add_u32 s8, s94, 0x1d800000
	s_addc_u32 s9, s95, 0
	s_lshl_b32 s31, s39, 21
	s_add_u32 s8, s8, s31
	s_addc_u32 s9, s9, 0
	s_lshl_b32 s31, s40, 8
	s_add_u32 s8, s8, s31
	s_addc_u32 s9, s9, 0
	s_add_u32 s10, s94, 0x2f00000
	s_addc_u32 s11, s95, 0
	s_lshl_b32 s31, s37, 18
	s_add_u32 s10, s10, s31
	s_addc_u32 s11, s11, 0
	s_add_u32 s12, s94, 0x3700000
	s_addc_u32 s13, s95, 0
	s_lshl_b32 s31, s37, 19
	s_add_u32 s12, s12, s31
	s_addc_u32 s13, s13, 0
	s_mov_b32 m0, s46
	s_nop 0
	global_load_lds_dwordx4 v255, s[8:9]
	s_add_i32 m0, s46, 0x400
	s_nop 0
	global_load_lds_dwordx4 v254, s[8:9]
	s_mov_b32 m0, s47
	s_nop 0
	global_load_lds_dwordx4 v253, s[10:11]
	s_mov_b32 m0, s48
	s_nop 0
	global_load_lds_dwordx4 v252, s[12:13]
	s_add_i32 m0, s48, 0x400
	s_nop 0
	global_load_lds_dwordx4 v251, s[12:13]
	s_add_u32 s8, s8, 0x10000
	s_addc_u32 s9, s9, 0
	s_add_u32 s10, s10, 0x2000
	s_addc_u32 s11, s11, 0
	s_add_u32 s12, s12, 0x4000
	s_addc_u32 s13, s13, 0
	s_add_i32 m0, s46, 0xa000
	s_nop 0
	global_load_lds_dwordx4 v255, s[8:9]
	s_add_i32 m0, s46, 0xa400
	s_nop 0
	global_load_lds_dwordx4 v254, s[8:9]
	s_add_i32 m0, s47, 0xa000
	s_nop 0
	global_load_lds_dwordx4 v253, s[10:11]
	s_add_i32 m0, s48, 0xa000
	s_nop 0
	global_load_lds_dwordx4 v252, s[12:13]
	s_add_i32 m0, s48, 0xa400
	s_nop 0
	global_load_lds_dwordx4 v251, s[12:13]
	s_add_u32 s8, s8, 0x10000
	s_addc_u32 s9, s9, 0
	s_add_u32 s10, s10, 0x2000
	s_addc_u32 s11, s11, 0
	s_add_u32 s12, s12, 0x4000
	s_addc_u32 s13, s13, 0
	s_mov_b32 s49, 1
	v_and_b32_e32 v200, 1, v163
	v_lshl_add_u32 v200, v200, 5, v202
	v_or_b32_e32 v199, 0, v201
	v_and_b32_e32 v198, 15, v200
	v_xor_b32_e32 v199, v199, v198
	v_lshlrev_b32_e32 v241, 8, v200
	v_lshl_add_u32 v241, v199, 4, v241
	v_or_b32_e32 v199, 4, v201
	v_and_b32_e32 v198, 15, v200
	v_xor_b32_e32 v199, v199, v198
	v_lshlrev_b32_e32 v240, 8, v200
	v_lshl_add_u32 v240, v199, 4, v240
	v_or_b32_e32 v199, 8, v201
	v_and_b32_e32 v198, 15, v200
	v_xor_b32_e32 v199, v199, v198
	v_lshlrev_b32_e32 v239, 8, v200
	v_lshl_add_u32 v239, v199, 4, v239
	v_or_b32_e32 v199, 12, v201
	v_and_b32_e32 v198, 15, v200
	v_xor_b32_e32 v199, v199, v198
	v_lshlrev_b32_e32 v238, 8, v200
	v_lshl_add_u32 v238, v199, 4, v238
	v_or_b32_e32 v199, 0, v201
	v_bfe_u32 v198, v200, 1, 3
	v_xor_b32_e32 v199, v199, v198
	v_lshlrev_b32_e32 v231, 7, v200
	v_lshl_add_u32 v231, v199, 4, v231
	v_add_u32_e32 v231, 0x4000, v231
	v_or_b32_e32 v199, 4, v201
	v_bfe_u32 v198, v200, 1, 3
	v_xor_b32_e32 v199, v199, v198
	v_lshlrev_b32_e32 v230, 7, v200
	v_lshl_add_u32 v230, v199, 4, v230
	v_add_u32_e32 v230, 0x4000, v230
	v_lshlrev_b32_e32 v248, 11, v200
	v_lshl_add_u32 v248, v201, 3, v248
	v_add_u32_e32 v247, 0x8000, v248
	v_or_b32_e32 v199, 0, v201
	v_and_b32_e32 v198, 15, v202
	v_xor_b32_e32 v199, v199, v198
	v_lshlrev_b32_e32 v223, 8, v202
	v_lshl_add_u32 v223, v199, 4, v223
	v_add_u32_e32 v223, 0x1e000, v223
	v_or_b32_e32 v199, 4, v201
	v_and_b32_e32 v198, 15, v202
	v_xor_b32_e32 v199, v199, v198
	v_lshlrev_b32_e32 v222, 8, v202
	v_lshl_add_u32 v222, v199, 4, v222
	v_add_u32_e32 v222, 0x1e000, v222
	v_or_b32_e32 v199, 8, v201
	v_and_b32_e32 v198, 15, v202
	v_xor_b32_e32 v199, v199, v198
	v_lshlrev_b32_e32 v221, 8, v202
	v_lshl_add_u32 v221, v199, 4, v221
	v_add_u32_e32 v221, 0x1e000, v221
	v_or_b32_e32 v199, 12, v201
	v_and_b32_e32 v198, 15, v202
	v_xor_b32_e32 v199, v199, v198
	v_lshlrev_b32_e32 v220, 8, v202
	v_lshl_add_u32 v220, v199, 4, v220
	v_add_u32_e32 v220, 0x1e000, v220
	v_or_b32_e32 v199, 0, v201
	v_bfe_u32 v198, v202, 1, 3
	v_xor_b32_e32 v199, v199, v198
	v_lshlrev_b32_e32 v219, 7, v202
	v_lshl_add_u32 v219, v199, 4, v219
	v_add_u32_e32 v219, 0x20100, v219
	v_or_b32_e32 v199, 4, v201
	v_bfe_u32 v198, v202, 1, 3
	v_xor_b32_e32 v199, v199, v198
	v_lshlrev_b32_e32 v218, 7, v202
	v_lshl_add_u32 v218, v199, 4, v218
	v_add_u32_e32 v218, 0x20100, v218
	v_and_b32_e32 v200, 1, v163
	v_lshl_add_u32 v200, v200, 6, v202
	v_or_b32_e32 v199, 0, v201
	v_bfe_u32 v198, v200, 1, 3
	v_xor_b32_e32 v199, v199, v198
	v_lshlrev_b32_e32 v227, 7, v200
	v_lshl_add_u32 v227, v199, 4, v227
	v_add_u32_e32 v227, 0x6000, v227
	v_or_b32_e32 v199, 4, v201
	v_bfe_u32 v198, v200, 1, 3
	v_xor_b32_e32 v199, v199, v198
	v_lshlrev_b32_e32 v226, 7, v200
	v_lshl_add_u32 v226, v199, 4, v226
	v_add_u32_e32 v226, 0x6000, v226
	v_or_b32_e32 v199, 0, v201
	v_bfe_u32 v198, v202, 1, 3
	v_xor_b32_e32 v199, v199, v198
	v_lshlrev_b32_e32 v217, 7, v202
	v_lshl_add_u32 v217, v199, 4, v217
	v_add_u32_e32 v217, 0x20100, v217
	v_or_b32_e32 v199, 4, v201
	v_bfe_u32 v198, v202, 1, 3
	v_xor_b32_e32 v199, v199, v198
	v_lshlrev_b32_e32 v216, 7, v202
	v_lshl_add_u32 v216, v199, 4, v216
	v_add_u32_e32 v216, 0x20100, v216
	v_add_u32_e32 v235, 0x14000, v241
	v_add_u32_e32 v234, 0x14000, v240
	v_add_u32_e32 v233, 0x14000, v239
	v_add_u32_e32 v232, 0x14000, v238
	v_add_u32_e32 v229, 0x14000, v231
	v_add_u32_e32 v228, 0x14000, v230
	v_add_u32_e32 v225, 0x14000, v227
	v_add_u32_e32 v224, 0x14000, v226
	v_and_b32_e32 v200, 1, v163
	v_lshrrev_b32_e32 v199, 1, v201
	v_lshl_add_u32 v199, v200, 3, v199
	v_xor_b32_e32 v199, v199, v202
	v_lshlrev_b32_e32 v215, 8, v202
	v_lshl_add_u32 v215, v199, 4, v215
	v_and_b32_e32 v199, 1, v201
	v_lshl_add_u32 v215, v199, 3, v215
	v_add_u32_e32 v215, 0x1e000, v215
	v_and_b32_e32 v200, 1, v163
	v_lshrrev_b32_e32 v199, 1, v201
	v_lshl_add_u32 v199, v200, 3, v199
	v_add_u32_e32 v199, 2, v199
	v_xor_b32_e32 v199, v199, v202
	v_lshlrev_b32_e32 v214, 8, v202
	v_lshl_add_u32 v214, v199, 4, v214
	v_and_b32_e32 v199, 1, v201
	v_lshl_add_u32 v214, v199, 3, v214
	v_add_u32_e32 v214, 0x1e000, v214
	v_and_b32_e32 v200, 1, v163
	v_lshrrev_b32_e32 v199, 1, v201
	v_lshl_add_u32 v199, v200, 3, v199
	v_add_u32_e32 v199, 4, v199
	v_xor_b32_e32 v199, v199, v202
	v_lshlrev_b32_e32 v213, 8, v202
	v_lshl_add_u32 v213, v199, 4, v213
	v_and_b32_e32 v199, 1, v201
	v_lshl_add_u32 v213, v199, 3, v213
	v_add_u32_e32 v213, 0x1e000, v213
	v_and_b32_e32 v200, 1, v163
	v_lshrrev_b32_e32 v199, 1, v201
	v_lshl_add_u32 v199, v200, 3, v199
	v_add_u32_e32 v199, 6, v199
	v_xor_b32_e32 v199, v199, v202
	v_lshlrev_b32_e32 v212, 8, v202
	v_lshl_add_u32 v212, v199, 4, v212
	v_and_b32_e32 v199, 1, v201
	v_lshl_add_u32 v212, v199, 3, v212
	v_add_u32_e32 v212, 0x1e000, v212
	v_bfe_u32 v200, v162, 2, 6
	v_and_b32_e32 v198, 3, v162
	v_lshl_add_u32 v199, v198, 3, 0
	v_lshlrev_b32_e32 v211, 7, v199
	v_bfe_u32 v199, v199, 1, 3
	v_lshrrev_b32_e32 v246, 3, v200
	v_xor_b32_e32 v199, v199, v246
	v_lshl_add_u32 v211, v199, 4, v211
	v_and_b32_e32 v199, 7, v200
	v_lshl_add_u32 v211, v199, 1, v211
	v_add_u32_e32 v211, 0x20100, v211
	v_lshl_add_u32 v199, v198, 3, 1
	v_lshlrev_b32_e32 v210, 7, v199
	v_bfe_u32 v199, v199, 1, 3
	v_lshrrev_b32_e32 v246, 3, v200
	v_xor_b32_e32 v199, v199, v246
	v_lshl_add_u32 v210, v199, 4, v210
	v_and_b32_e32 v199, 7, v200
	v_lshl_add_u32 v210, v199, 1, v210
	v_add_u32_e32 v210, 0x20100, v210
	v_lshl_add_u32 v199, v198, 3, 2
	v_lshlrev_b32_e32 v209, 7, v199
	v_bfe_u32 v199, v199, 1, 3
	v_lshrrev_b32_e32 v246, 3, v200
	v_xor_b32_e32 v199, v199, v246
	v_lshl_add_u32 v209, v199, 4, v209
	v_and_b32_e32 v199, 7, v200
	v_lshl_add_u32 v209, v199, 1, v209
	v_add_u32_e32 v209, 0x20100, v209
	v_lshl_add_u32 v199, v198, 3, 3
	v_lshlrev_b32_e32 v208, 7, v199
	v_bfe_u32 v199, v199, 1, 3
	v_lshrrev_b32_e32 v246, 3, v200
	v_xor_b32_e32 v199, v199, v246
	v_lshl_add_u32 v208, v199, 4, v208
	v_and_b32_e32 v199, 7, v200
	v_lshl_add_u32 v208, v199, 1, v208
	v_add_u32_e32 v208, 0x20100, v208
	v_lshl_add_u32 v199, v198, 3, 4
	v_lshlrev_b32_e32 v207, 7, v199
	v_bfe_u32 v199, v199, 1, 3
	v_lshrrev_b32_e32 v246, 3, v200
	v_xor_b32_e32 v199, v199, v246
	v_lshl_add_u32 v207, v199, 4, v207
	v_and_b32_e32 v199, 7, v200
	v_lshl_add_u32 v207, v199, 1, v207
	v_add_u32_e32 v207, 0x20100, v207
	v_lshl_add_u32 v199, v198, 3, 5
	v_lshlrev_b32_e32 v206, 7, v199
	v_bfe_u32 v199, v199, 1, 3
	v_lshrrev_b32_e32 v246, 3, v200
	v_xor_b32_e32 v199, v199, v246
	v_lshl_add_u32 v206, v199, 4, v206
	v_and_b32_e32 v199, 7, v200
	v_lshl_add_u32 v206, v199, 1, v206
	v_add_u32_e32 v206, 0x20100, v206
	v_lshl_add_u32 v199, v198, 3, 6
	v_lshlrev_b32_e32 v205, 7, v199
	v_bfe_u32 v199, v199, 1, 3
	v_lshrrev_b32_e32 v246, 3, v200
	v_xor_b32_e32 v199, v199, v246
	v_lshl_add_u32 v205, v199, 4, v205
	v_and_b32_e32 v199, 7, v200
	v_lshl_add_u32 v205, v199, 1, v205
	v_add_u32_e32 v205, 0x20100, v205
	v_lshl_add_u32 v199, v198, 3, 7
	v_lshlrev_b32_e32 v204, 7, v199
	v_bfe_u32 v199, v199, 1, 3
	v_lshrrev_b32_e32 v246, 3, v200
	v_xor_b32_e32 v199, v199, v246
	v_lshl_add_u32 v204, v199, 4, v204
	v_and_b32_e32 v199, 7, v200
	v_lshl_add_u32 v204, v199, 1, v204
	v_add_u32_e32 v204, 0x20100, v204
	v_bfe_u32 v200, v162, 2, 6
	v_and_b32_e32 v199, 3, v162
	v_lshlrev_b32_e32 v250, 14, v200
	v_lshl_add_u32 v250, v199, 4, v250
	v_and_b32_e32 v200, 1, v163
	v_lshlrev_b32_e32 v249, 8, v200
	v_lshl_add_u32 v249, v201, 4, v249
	v_and_b32_e32 v199, 3, v202
	v_lshl_add_u32 v249, v199, 6, v249
	v_lshlrev_b32_e32 v245, 16, v200
	v_lshl_add_u32 v245, v201, 12, v245
	v_lshl_add_u32 v245, v202, 2, v245
	v_add_u32_e32 v244, 0x4000, v245
	v_add_u32_e32 v243, 0x8000, v245
	v_add_u32_e32 v242, 0xc000, v245
	v_lshlrev_b32_e32 v246, 4, v162
	v_add_u32_e32 v246, 0x1e000, v246
	v_mov_b32_e32 v8, 0
	v_mov_b32_e32 v9, 0
	v_mov_b32_e32 v10, 0
	v_mov_b32_e32 v11, 0
	s_cmp_gt_u32 s32, 3
	s_cbranch_scc1 .Lp3V_entry
	s_cmp_gt_u32 s32, 1
	s_cbranch_scc1 .Lp3S_entry

; #define LAS __attribute__((address_space(3)))
; __device__ __forceinline__ void gla_scan_item(const Ctx& C, int item, LAS unsigned char* lds, int tid) {
;     ...
;     f32x4 S[2] = {(f32x4){0.f, 0.f, 0.f, 0.f}, (f32x4){0.f, 0.f, 0.f, 0.f}};
;     *(LAS u32x4*)(Bc + (tid >> 4) * 200 + (tid & 15) * 8) = (u32x4){0u, 0u, 0u, 0u};
;     u32x4 rq0A, rq1A, rsA, rk0A, rk1A, rvA = (u32x4){0u, 0u, 0u, 0u}; f32x4 rdA;
;     u32x4 rq0B, rq1B, rsB, rk0B, rk1B, rvB = (u32x4){0u, 0u, 0u, 0u}; f32x4 rdB;
;     ...
;     float* So = C.out + OUT_GLAP + ((size_t)bh * 128 + wave * 16 + quad * 4) * 256 + sl * 32 + l15;
.Lp3S_have:
	s_mov_b32 s49, 0
	s_add_u32 s16, s94, 0x2e00000
	s_addc_u32 s17, s95, 0
	s_lshl_b32 s31, s37, 14
	s_add_u32 s16, s16, s31
	s_addc_u32 s17, s17, 0
	s_add_u32 s34, s92, 0x4090000
	s_addc_u32 s35, s93, 0
	s_lshl_b32 s31, s37, 17
	s_add_u32 s34, s34, s31
	s_addc_u32 s35, s35, 0
	s_lshl_b32 s31, s41, 7
	s_add_u32 s34, s34, s31
	s_addc_u32 s35, s35, 0
	v_mov_b32_e32 v60, 0
	v_mov_b32_e32 v61, 0
	v_mov_b32_e32 v62, 0
	v_mov_b32_e32 v63, 0
	v_mov_b32_e32 v64, 0
	v_mov_b32_e32 v65, 0
	v_mov_b32_e32 v66, 0
	v_mov_b32_e32 v67, 0
	v_mov_b32_e32 v68, 0
	v_mov_b32_e32 v69, 0
	v_mov_b32_e32 v70, 0
	v_mov_b32_e32 v71, 0
	v_mov_b32_e32 v72, 0
	v_mov_b32_e32 v73, 0
	v_mov_b32_e32 v74, 0
	v_mov_b32_e32 v75, 0
	v_mov_b32_e32 v76, 0
	v_mov_b32_e32 v77, 0
	v_mov_b32_e32 v78, 0
	v_mov_b32_e32 v79, 0
	v_mov_b32_e32 v80, 0
	v_mov_b32_e32 v81, 0
	v_mov_b32_e32 v82, 0
	v_mov_b32_e32 v83, 0
	v_mov_b32_e32 v84, 0
	v_mov_b32_e32 v85, 0
	v_mov_b32_e32 v86, 0
	v_mov_b32_e32 v87, 0
	v_mov_b32_e32 v88, 0
	v_mov_b32_e32 v89, 0
	v_mov_b32_e32 v90, 0
	v_mov_b32_e32 v91, 0
	ds_write_b128 v246, v[8:11]
	global_load_dwordx4 v[92:95], v249, s[16:17]
	s_add_u32 s16, s16, 0x200
	s_addc_u32 s17, s17, 0
	global_load_dwordx4 v[108:111], v249, s[16:17]
	s_add_u32 s16, s16, 0x200
	s_addc_u32 s17, s17, 0
	global_load_dwordx4 v[124:127], v249, s[16:17]
	s_add_u32 s16, s16, 0x200
	s_addc_u32 s17, s17, 0
	s_waitcnt vmcnt(0)
	s_mov_b32 s33, 0
	s_waitcnt lgkmcnt(0)
	s_barrier
